# attention tile body: V-fragment reads fill the MFMA-to-exp wait states (s_nop 1 + s_nop 7 -> 4 ds_reads + s_nop 5)
# speedup vs baseline: 1.0021x; 1.0021x over previous
.LBB0_319:
	s_add_i32 s6, s39, 0xfffe8000
	s_and_b32 s6, s6, 0x18000
	s_add_i32 s12, s6, 0
	s_add_i32 s6, s12, s40
	v_add_u32_e32 v76, s6, v164
	s_lshl_b32 s6, s3, 6
	v_cvt_f32_i32_e32 v80, s6
	v_add_u32_e32 v68, v76, v163
	v_add_u32_e32 v72, v76, v165
	v_add_u32_e32 v77, v76, v166
	v_add_u32_e32 v81, v76, v167
	ds_read_b128 v[64:67], v68
	ds_read_b128 v[114:117], v68 offset:4096
	ds_read_b128 v[68:71], v72
	ds_read_b128 v[124:127], v72 offset:4096
	ds_read_b128 v[72:75], v77
	ds_read_b128 v[134:137], v77 offset:4096
	ds_read_b128 v[76:79], v81
	ds_read_b128 v[120:123], v81 offset:4096
	s_cmp_lt_i32 s3, s24
	s_cselect_b64 s[6:7], -1, 0
	v_sub_f32_e32 v113, v170, v80
	v_cndmask_b32_e64 v118, -v156, v156, s[6:7]
	v_mul_f32_e32 v119, 0x41000000, v118
	v_fma_f32 v80, v118, -v113, -v155
	v_add_f32_e32 v84, v119, v80
	v_add_f32_e32 v81, v118, v80
	v_add_f32_e32 v88, v119, v84
	v_add_f32_e32 v82, v118, v81
	v_add_f32_e32 v85, v118, v84
	v_add_f32_e32 v92, v119, v88
	v_add_f32_e32 v83, v118, v82
	v_add_f32_e32 v86, v118, v85
	v_add_f32_e32 v89, v118, v88
	v_add_f32_e32 v87, v118, v86
	v_add_f32_e32 v90, v118, v89
	v_add_f32_e32 v93, v118, v92
	v_add_f32_e32 v91, v118, v90
	v_add_f32_e32 v94, v118, v93
	v_add_f32_e32 v95, v118, v94
	s_nop 1
	s_waitcnt lgkmcnt(7)
	v_mfma_f32_32x32x16_bf16 v[80:95], v[64:67], v[96:99], v[80:95]
	v_sub_f32_e32 v64, 0x42000000, v113
	v_fma_f32 v64, v118, v64, -v155
	v_add_f32_e32 v65, v118, v64
	v_add_u32_e32 v132, s12, v162
	v_add_f32_e32 v66, v118, v65
	v_add_f32_e32 v67, v118, v66
	s_waitcnt lgkmcnt(5)
	v_mfma_f32_32x32x16_bf16 v[80:95], v[68:71], v[100:103], v[80:95]
	v_add_f32_e32 v68, v119, v64
	v_add_f32_e32 v69, v118, v68
	v_add_f32_e32 v70, v118, v69
	v_add_f32_e32 v71, v118, v70
	s_waitcnt lgkmcnt(3)
	v_mfma_f32_32x32x16_bf16 v[80:95], v[72:75], v[104:107], v[80:95]
	v_add_f32_e32 v72, v119, v68
	v_add_f32_e32 v73, v118, v72
	v_add_f32_e32 v74, v118, v73
	v_add_f32_e32 v75, v118, v74
	s_waitcnt lgkmcnt(1)
	v_mfma_f32_32x32x16_bf16 v[80:95], v[76:79], v[108:111], v[80:95]
	v_add_f32_e32 v76, v119, v72
	v_add_f32_e32 v77, v118, v76
	v_add_f32_e32 v78, v118, v77
	v_add_f32_e32 v79, v118, v78
	ds_read_b64_tr_b16 v[138:139], v132 offset:16384
	ds_read_b64_tr_b16 v[140:141], v132 offset:16896
	ds_read_b64_tr_b16 v[142:143], v132 offset:17408
	ds_read_b64_tr_b16 v[144:145], v132 offset:17920
	s_nop 5
	v_exp_f32_e32 v80, v80
	v_exp_f32_e32 v81, v81
	v_exp_f32_e32 v82, v82
	v_exp_f32_e32 v83, v83
	v_add_f32_e32 v112, v112, v80
	v_add_f32_e32 v112, v81, v112
	v_add_f32_e32 v112, v82, v112
	v_add_f32_e32 v112, v83, v112
	v_mfma_f32_32x32x16_bf16 v[64:79], v[114:117], v[96:99], v[64:79]
	ds_read_b64_tr_b16 v[158:159], v132 offset:20480
	ds_read_b64_tr_b16 v[160:161], v132 offset:20992
	ds_read_b64_tr_b16 v[172:173], v132 offset:21504
	ds_read_b64_tr_b16 v[174:175], v132 offset:22016
	v_exp_f32_e32 v133, v84
	v_exp_f32_e32 v146, v85
	v_exp_f32_e32 v147, v86
	v_exp_f32_e32 v171, v87
	v_add_f32_e32 v84, v133, v112
	v_add_f32_e32 v84, v146, v84
	v_add_f32_e32 v84, v147, v84
	v_add_f32_e32 v84, v171, v84
	v_mfma_f32_32x32x16_bf16 v[64:79], v[124:127], v[100:103], v[64:79]
	ds_read_b64_tr_b16 v[124:125], v132 offset:24576
	ds_read_b64_tr_b16 v[126:127], v132 offset:25088
	ds_read_b64_tr_b16 v[116:117], v132 offset:25600
	ds_read_b64_tr_b16 v[118:119], v132 offset:26112
	v_exp_f32_e32 v88, v88
	v_exp_f32_e32 v89, v89
	v_exp_f32_e32 v90, v90
	v_exp_f32_e32 v91, v91
	v_add_f32_e32 v84, v88, v84
	v_add_f32_e32 v84, v89, v84
	v_add_f32_e32 v84, v90, v84
	v_add_f32_e32 v176, v91, v84
	v_mfma_f32_32x32x16_bf16 v[64:79], v[134:137], v[104:107], v[64:79]
	ds_read_b64_tr_b16 v[112:113], v132 offset:28672
	ds_read_b64_tr_b16 v[114:115], v132 offset:29184
	ds_read_b64_tr_b16 v[84:85], v132 offset:29696
	ds_read_b64_tr_b16 v[86:87], v132 offset:30208
	v_exp_f32_e32 v134, v92
	v_exp_f32_e32 v135, v93
	v_exp_f32_e32 v136, v94
	v_exp_f32_e32 v95, v95
	v_add_f32_e32 v92, v134, v176
	v_add_f32_e32 v92, v135, v92
	v_add_f32_e32 v92, v136, v92
	v_add_f32_e32 v137, v95, v92
	s_waitcnt lgkmcnt(14)
	v_mfma_f32_32x32x16_bf16 v[64:79], v[120:123], v[108:111], v[64:79]
	v_cvt_pk_bf16_f32 v120, v80, v81
	v_cvt_pk_bf16_f32 v121, v82, v83
	v_cvt_pk_bf16_f32 v122, v133, v146
	v_cvt_pk_bf16_f32 v123, v147, v171
	v_cvt_pk_bf16_f32 v92, v88, v89
	v_cvt_pk_bf16_f32 v93, v90, v91
	v_cvt_pk_bf16_f32 v94, v134, v135
	v_cvt_pk_bf16_f32 v95, v136, v95
	v_mfma_f32_32x32x16_bf16 v[0:15], v[138:141], v[120:123], v[0:15]
	ds_read_b64_tr_b16 v[80:81], v132 offset:18432
	ds_read_b64_tr_b16 v[82:83], v132 offset:18944
	s_nop 0
	v_exp_f32_e32 v133, v64
	v_exp_f32_e32 v138, v65
	v_add_f32_e32 v64, v137, v133
	v_add_f32_e32 v64, v138, v64
	s_waitcnt lgkmcnt(14)
	v_mfma_f32_32x32x16_bf16 v[0:15], v[142:145], v[92:95], v[0:15]
	ds_read_b64_tr_b16 v[88:89], v132 offset:19456
	ds_read_b64_tr_b16 v[90:91], v132 offset:19968
	v_exp_f32_e32 v139, v66
	v_exp_f32_e32 v140, v67
	v_add_f32_e32 v64, v139, v64
	v_add_f32_e32 v134, v140, v64
	s_waitcnt lgkmcnt(14)
	v_mfma_f32_32x32x16_bf16 v[16:31], v[158:161], v[120:123], v[16:31]
	ds_read_b64_tr_b16 v[64:65], v132 offset:22528
	ds_read_b64_tr_b16 v[66:67], v132 offset:23040
	v_exp_f32_e32 v141, v68
	v_exp_f32_e32 v142, v69
	v_add_f32_e32 v68, v141, v134
	v_add_f32_e32 v68, v142, v68
	s_waitcnt lgkmcnt(14)
	v_mfma_f32_32x32x16_bf16 v[16:31], v[172:175], v[92:95], v[16:31]
	ds_read_b64_tr_b16 v[134:135], v132 offset:23552
	ds_read_b64_tr_b16 v[136:137], v132 offset:24064
	v_exp_f32_e32 v143, v70
	v_exp_f32_e32 v144, v71
	v_add_f32_e32 v68, v143, v68
	v_add_f32_e32 v145, v144, v68
	s_waitcnt lgkmcnt(14)
	v_mfma_f32_32x32x16_bf16 v[32:47], v[124:127], v[120:123], v[32:47]
	ds_read_b64_tr_b16 v[68:69], v132 offset:26624
	ds_read_b64_tr_b16 v[70:71], v132 offset:27136
	v_exp_f32_e32 v124, v72
	v_exp_f32_e32 v125, v73
	v_add_f32_e32 v72, v124, v145
	v_add_f32_e32 v72, v125, v72
	s_waitcnt lgkmcnt(14)
	v_mfma_f32_32x32x16_bf16 v[32:47], v[116:119], v[92:95], v[32:47]
	ds_read_b64_tr_b16 v[116:117], v132 offset:27648
	ds_read_b64_tr_b16 v[118:119], v132 offset:28160
	v_exp_f32_e32 v126, v74
	v_exp_f32_e32 v127, v75
	v_add_f32_e32 v72, v126, v72
	v_add_f32_e32 v145, v127, v72
	s_waitcnt lgkmcnt(14)
	v_mfma_f32_32x32x16_bf16 v[48:63], v[112:115], v[120:123], v[48:63]
	ds_read_b64_tr_b16 v[72:73], v132 offset:30720
	ds_read_b64_tr_b16 v[74:75], v132 offset:31232
	v_exp_f32_e32 v113, v76
	v_exp_f32_e32 v114, v77
	v_add_f32_e32 v76, v113, v145
	v_add_f32_e32 v76, v114, v76
	s_waitcnt lgkmcnt(14)
	v_mfma_f32_32x32x16_bf16 v[48:63], v[84:87], v[92:95], v[48:63]
	v_exp_f32_e32 v95, v78
	ds_read_b64_tr_b16 v[84:85], v132 offset:31744
	ds_read_b64_tr_b16 v[86:87], v132 offset:32256
	v_exp_f32_e32 v115, v79
	v_add_f32_e32 v76, v95, v76
	v_add_f32_e32 v112, v115, v76
	v_cvt_pk_bf16_f32 v76, v133, v138
	v_cvt_pk_bf16_f32 v77, v139, v140
	v_cvt_pk_bf16_f32 v78, v141, v142
	v_cvt_pk_bf16_f32 v79, v143, v144
	v_cvt_pk_bf16_f32 v92, v124, v125
	v_cvt_pk_bf16_f32 v93, v126, v127
	v_cvt_pk_bf16_f32 v94, v113, v114
	v_cvt_pk_bf16_f32 v95, v95, v115
	s_setprio 0
	s_bitcmp1_b32 s26, 0
	s_cbranch_scc1 .Lda_dplain
	s_cmp_ge_i32 s26, s34
	s_cbranch_scc1 .Lda_dplain
	s_add_i32 s100, s26, 2
	s_and_b32 s100, s100, 3
	s_lshl_b32 s100, s100, 15
	s_add_i32 s101, s100, s43
	s_waitcnt lgkmcnt(14)
	v_mfma_f32_32x32x16_bf16 v[0:15], v[80:83], v[76:79], v[0:15]
	s_mov_b32 m0, s101
	s_addk_i32 s101, 0x2000
	global_load_lds_dwordx4 v[186:187], off
	s_waitcnt lgkmcnt(10)
	v_mfma_f32_32x32x16_bf16 v[16:31], v[64:67], v[76:79], v[16:31]
	s_mov_b32 m0, s101
	s_add_i32 s101, s100, s45
	global_load_lds_dwordx4 v[188:189], off
	s_waitcnt lgkmcnt(6)
	v_mfma_f32_32x32x16_bf16 v[32:47], v[68:71], v[76:79], v[32:47]
	s_mov_b32 m0, s101
	s_add_i32 s101, s100, s46
	global_load_lds_dwordx4 v[190:191], off
	s_waitcnt lgkmcnt(2)
	v_mfma_f32_32x32x16_bf16 v[48:63], v[72:75], v[76:79], v[48:63]
	s_mov_b32 m0, s101
	s_add_i32 s100, s100, 0x8000
	global_load_lds_dwordx4 v[192:193], off
	s_add_i32 s101, s100, s43
	v_mfma_f32_32x32x16_bf16 v[0:15], v[88:91], v[92:95], v[0:15]
	s_mov_b32 m0, s101
	s_addk_i32 s101, 0x2000
	global_load_lds_dwordx4 v[194:195], off
	v_mfma_f32_32x32x16_bf16 v[16:31], v[134:137], v[92:95], v[16:31]
	s_mov_b32 m0, s101
	s_add_i32 s101, s100, s45
	global_load_lds_dwordx4 v[196:197], off
	v_mfma_f32_32x32x16_bf16 v[32:47], v[116:119], v[92:95], v[32:47]
	s_mov_b32 m0, s101
	s_add_i32 s101, s100, s46
	global_load_lds_dwordx4 v[198:199], off
	s_waitcnt lgkmcnt(0)
	v_mfma_f32_32x32x16_bf16 v[48:63], v[84:87], v[92:95], v[48:63]
	s_mov_b32 m0, s101
	s_nop 0
	global_load_lds_dwordx4 v[200:201], off
	s_branch .Lda_dend
